# P8 row pass (non-fused FFN pre-norm): next-row loads prefetched, g_ffn hoisted, one counted wait per row
# speedup vs baseline: 1.0073x; 1.0053x over previous
.LBB0_989:
	s_or_b64 exec, exec, s[0:1]
	v_readlane_b32 s0, v254, 23
	v_readlane_b32 s1, v254, 24
	s_and_b64 vcc, exec, s[0:1]
	v_readlane_b32 s12, v254, 47
	s_waitcnt lgkmcnt(0)
	s_barrier
	v_mbcnt_lo_u32_b32 v0, -1, 0
	v_mbcnt_hi_u32_b32 v0, -1, v0
	v_readlane_b32 s13, v254, 48
	s_cbranch_vccz .LBB0_992
	v_and_b32_e32 v0, 63, v0
	v_readlane_b32 s1, v254, 21
	v_lshlrev_b32_e32 v1, 4, v0
	v_lshlrev_b32_e32 v2, 3, v0
	v_mov_b32_e32 v3, 0x358637bd
	v_add_u32_e32 v4, 0x1000, v1
	global_load_dwordx4 v[10:13], v1, s[58:59]
	global_load_dwordx4 v[14:17], v1, s[58:59] offset:1024
	global_load_dwordx4 v[18:21], v1, s[58:59] offset:2048
	global_load_dwordx4 v[22:25], v1, s[58:59] offset:3072
	s_lshl_b32 s0, s1, 12
	s_add_u32 s4, s68, s0
	s_addc_u32 s5, s69, 0
	s_ashr_i32 s0, s1, 12
	s_mul_i32 s0, s0, 0x6000
	s_add_i32 s0, s0, 0x3000
	s_add_u32 s6, s70, s0
	s_addc_u32 s7, s71, 0
	global_load_dwordx4 v[26:29], v1, s[4:5] nt
	global_load_dwordx4 v[30:33], v1, s[4:5] offset:1024 nt
	global_load_dwordx4 v[34:37], v1, s[4:5] offset:2048 nt
	global_load_dwordx4 v[38:41], v1, s[4:5] offset:3072 nt
	global_load_dwordx4 v[58:61], v1, s[6:7]
	global_load_dwordx4 v[62:65], v1, s[6:7] offset:1024
	global_load_dwordx4 v[66:69], v1, s[6:7] offset:2048
	global_load_dwordx4 v[70:73], v1, s[6:7] offset:3072
	global_load_dwordx4 v[74:77], v4, s[6:7]
	global_load_dwordx4 v[78:81], v4, s[6:7] offset:1024
	global_load_dwordx4 v[82:85], v4, s[6:7] offset:2048
	global_load_dwordx4 v[86:89], v4, s[6:7] offset:3072
.Lp8_loop:
	s_lshl_b32 s0, s1, 11
	s_add_u32 s8, s70, 0x13000000
	s_addc_u32 s9, s71, 0
	s_add_u32 s8, s8, s0
	s_addc_u32 s9, s9, 0
	s_add_i32 s10, s1, s12
	s_cmp_lt_i32 s10, 0x8000
	s_cbranch_scc0 .Lp8_last_0
	s_lshl_b32 s0, s10, 12
	s_add_u32 s4, s68, s0
	s_addc_u32 s5, s69, 0
	s_ashr_i32 s0, s10, 12
	s_mul_i32 s0, s0, 0x6000
	s_add_i32 s0, s0, 0x3000
	s_add_u32 s6, s70, s0
	s_addc_u32 s7, s71, 0
	global_load_dwordx4 v[42:45], v1, s[4:5] nt
	global_load_dwordx4 v[46:49], v1, s[4:5] offset:1024 nt
	global_load_dwordx4 v[50:53], v1, s[4:5] offset:2048 nt
	global_load_dwordx4 v[54:57], v1, s[4:5] offset:3072 nt
	global_load_dwordx4 v[90:93], v1, s[6:7]
	global_load_dwordx4 v[94:97], v1, s[6:7] offset:1024
	global_load_dwordx4 v[98:101], v1, s[6:7] offset:2048
	global_load_dwordx4 v[102:105], v1, s[6:7] offset:3072
	global_load_dwordx4 v[106:109], v4, s[6:7]
	global_load_dwordx4 v[110:113], v4, s[6:7] offset:1024
	global_load_dwordx4 v[114:117], v4, s[6:7] offset:2048
	global_load_dwordx4 v[118:121], v4, s[6:7] offset:3072
	s_waitcnt vmcnt(12)
	v_mul_f32_e32 v122, v26, v26
	v_fmac_f32_e32 v122, v27, v27
	v_fmac_f32_e32 v122, v28, v28
	v_fmac_f32_e32 v122, v29, v29
	v_mul_f32_e32 v123, v30, v30
	v_fmac_f32_e32 v123, v31, v31
	v_fmac_f32_e32 v123, v32, v32
	v_fmac_f32_e32 v123, v33, v33
	v_mul_f32_e32 v124, v34, v34
	v_fmac_f32_e32 v124, v35, v35
	v_fmac_f32_e32 v124, v36, v36
	v_fmac_f32_e32 v124, v37, v37
	v_mul_f32_e32 v125, v38, v38
	v_fmac_f32_e32 v125, v39, v39
	v_fmac_f32_e32 v125, v40, v40
	v_fmac_f32_e32 v125, v41, v41
	v_add_f32_e32 v122, v122, v123
	v_add_f32_e32 v124, v124, v125
	v_add_f32_e32 v122, v122, v124
	s_nop 1
	v_add_f32_dpp v122, v122, v122 quad_perm:[1,0,3,2] row_mask:0xf bank_mask:0xf bound_ctrl:1
	s_nop 1
	v_add_f32_dpp v122, v122, v122 quad_perm:[2,3,0,1] row_mask:0xf bank_mask:0xf bound_ctrl:1
	s_nop 1
	v_add_f32_dpp v122, v122, v122 row_half_mirror row_mask:0xf bank_mask:0xf bound_ctrl:1
	s_nop 1
	v_add_f32_dpp v122, v122, v122 row_mirror row_mask:0xf bank_mask:0xf bound_ctrl:1
	v_mov_b32_e32 v123, v122
	s_nop 1
	v_permlane16_swap_b32_e32 v122, v123
	v_add_f32_e32 v122, v122, v123
	v_mov_b32_e32 v123, v122
	s_nop 1
	v_permlane32_swap_b32_e32 v122, v123
	v_add_f32_e32 v122, v122, v123
	v_fmamk_f32 v122, v122, 0x3a800000, v3
	v_rsq_f32_e32 v122, v122
	s_nop 0
	v_mov_b32_e32 v123, v122
	v_pk_mul_f32 v[26:27], v[122:123], v[26:27]
	v_pk_add_f32 v[74:75], v[74:75], 1.0 op_sel_hi:[1,0]
	v_pk_mul_f32 v[26:27], v[10:11], v[26:27]
	v_pk_fma_f32 v[26:27], v[74:75], v[26:27], v[58:59]
	v_pk_mul_f32 v[28:29], v[122:123], v[28:29]
	v_pk_add_f32 v[76:77], v[76:77], 1.0 op_sel_hi:[1,0]
	v_pk_mul_f32 v[28:29], v[12:13], v[28:29]
	v_pk_fma_f32 v[28:29], v[76:77], v[28:29], v[60:61]
	v_cvt_pk_bf16_f32 v124, v26, v27
	v_cvt_pk_bf16_f32 v125, v28, v29
	global_store_dwordx2 v2, v[124:125], s[8:9]
	v_pk_mul_f32 v[30:31], v[122:123], v[30:31]
	v_pk_add_f32 v[78:79], v[78:79], 1.0 op_sel_hi:[1,0]
	v_pk_mul_f32 v[30:31], v[14:15], v[30:31]
	v_pk_fma_f32 v[30:31], v[78:79], v[30:31], v[62:63]
	v_pk_mul_f32 v[32:33], v[122:123], v[32:33]
	v_pk_add_f32 v[80:81], v[80:81], 1.0 op_sel_hi:[1,0]
	v_pk_mul_f32 v[32:33], v[16:17], v[32:33]
	v_pk_fma_f32 v[32:33], v[80:81], v[32:33], v[64:65]
	v_cvt_pk_bf16_f32 v126, v30, v31
	v_cvt_pk_bf16_f32 v127, v32, v33
	global_store_dwordx2 v2, v[126:127], s[8:9] offset:512
	v_pk_mul_f32 v[34:35], v[122:123], v[34:35]
	v_pk_add_f32 v[82:83], v[82:83], 1.0 op_sel_hi:[1,0]
	v_pk_mul_f32 v[34:35], v[18:19], v[34:35]
	v_pk_fma_f32 v[34:35], v[82:83], v[34:35], v[66:67]
	v_pk_mul_f32 v[36:37], v[122:123], v[36:37]
	v_pk_add_f32 v[84:85], v[84:85], 1.0 op_sel_hi:[1,0]
	v_pk_mul_f32 v[36:37], v[20:21], v[36:37]
	v_pk_fma_f32 v[36:37], v[84:85], v[36:37], v[68:69]
	v_cvt_pk_bf16_f32 v124, v34, v35
	v_cvt_pk_bf16_f32 v125, v36, v37
	global_store_dwordx2 v2, v[124:125], s[8:9] offset:1024
	v_pk_mul_f32 v[38:39], v[122:123], v[38:39]
	v_pk_add_f32 v[86:87], v[86:87], 1.0 op_sel_hi:[1,0]
	v_pk_mul_f32 v[38:39], v[22:23], v[38:39]
	v_pk_fma_f32 v[38:39], v[86:87], v[38:39], v[70:71]
	v_pk_mul_f32 v[40:41], v[122:123], v[40:41]
	v_pk_add_f32 v[88:89], v[88:89], 1.0 op_sel_hi:[1,0]
	v_pk_mul_f32 v[40:41], v[24:25], v[40:41]
	v_pk_fma_f32 v[40:41], v[88:89], v[40:41], v[72:73]
	v_cvt_pk_bf16_f32 v126, v38, v39
	v_cvt_pk_bf16_f32 v127, v40, v41
	global_store_dwordx2 v2, v[126:127], s[8:9] offset:1536
	s_mov_b32 s1, s10
	s_branch .Lp8_next_0

.Lp8_next_0:
	s_lshl_b32 s0, s1, 11
	s_add_u32 s8, s70, 0x13000000
	s_addc_u32 s9, s71, 0
	s_add_u32 s8, s8, s0
	s_addc_u32 s9, s9, 0
	s_add_i32 s10, s1, s12
	s_cmp_lt_i32 s10, 0x8000
	s_cbranch_scc0 .Lp8_last_1
	s_lshl_b32 s0, s10, 12
	s_add_u32 s4, s68, s0
	s_addc_u32 s5, s69, 0
	s_ashr_i32 s0, s10, 12
	s_mul_i32 s0, s0, 0x6000
	s_add_i32 s0, s0, 0x3000
	s_add_u32 s6, s70, s0
	s_addc_u32 s7, s71, 0
	global_load_dwordx4 v[26:29], v1, s[4:5] nt
	global_load_dwordx4 v[30:33], v1, s[4:5] offset:1024 nt
	global_load_dwordx4 v[34:37], v1, s[4:5] offset:2048 nt
	global_load_dwordx4 v[38:41], v1, s[4:5] offset:3072 nt
	global_load_dwordx4 v[58:61], v1, s[6:7]
	global_load_dwordx4 v[62:65], v1, s[6:7] offset:1024
	global_load_dwordx4 v[66:69], v1, s[6:7] offset:2048
	global_load_dwordx4 v[70:73], v1, s[6:7] offset:3072
	global_load_dwordx4 v[74:77], v4, s[6:7]
	global_load_dwordx4 v[78:81], v4, s[6:7] offset:1024
	global_load_dwordx4 v[82:85], v4, s[6:7] offset:2048
	global_load_dwordx4 v[86:89], v4, s[6:7] offset:3072
	s_waitcnt vmcnt(12)
	v_mul_f32_e32 v122, v42, v42
	v_fmac_f32_e32 v122, v43, v43
	v_fmac_f32_e32 v122, v44, v44
	v_fmac_f32_e32 v122, v45, v45
	v_mul_f32_e32 v123, v46, v46
	v_fmac_f32_e32 v123, v47, v47
	v_fmac_f32_e32 v123, v48, v48
	v_fmac_f32_e32 v123, v49, v49
	v_mul_f32_e32 v124, v50, v50
	v_fmac_f32_e32 v124, v51, v51
	v_fmac_f32_e32 v124, v52, v52
	v_fmac_f32_e32 v124, v53, v53
	v_mul_f32_e32 v125, v54, v54
	v_fmac_f32_e32 v125, v55, v55
	v_fmac_f32_e32 v125, v56, v56
	v_fmac_f32_e32 v125, v57, v57
	v_add_f32_e32 v122, v122, v123
	v_add_f32_e32 v124, v124, v125
	v_add_f32_e32 v122, v122, v124
	s_nop 1
	v_add_f32_dpp v122, v122, v122 quad_perm:[1,0,3,2] row_mask:0xf bank_mask:0xf bound_ctrl:1
	s_nop 1
	v_add_f32_dpp v122, v122, v122 quad_perm:[2,3,0,1] row_mask:0xf bank_mask:0xf bound_ctrl:1
	s_nop 1
	v_add_f32_dpp v122, v122, v122 row_half_mirror row_mask:0xf bank_mask:0xf bound_ctrl:1
	s_nop 1
	v_add_f32_dpp v122, v122, v122 row_mirror row_mask:0xf bank_mask:0xf bound_ctrl:1
	v_mov_b32_e32 v123, v122
	s_nop 1
	v_permlane16_swap_b32_e32 v122, v123
	v_add_f32_e32 v122, v122, v123
	v_mov_b32_e32 v123, v122
	s_nop 1
	v_permlane32_swap_b32_e32 v122, v123
	v_add_f32_e32 v122, v122, v123
	v_fmamk_f32 v122, v122, 0x3a800000, v3
	v_rsq_f32_e32 v122, v122
	s_nop 0
	v_mov_b32_e32 v123, v122
	v_pk_mul_f32 v[42:43], v[122:123], v[42:43]
	v_pk_add_f32 v[106:107], v[106:107], 1.0 op_sel_hi:[1,0]
	v_pk_mul_f32 v[42:43], v[10:11], v[42:43]
	v_pk_fma_f32 v[42:43], v[106:107], v[42:43], v[90:91]
	v_pk_mul_f32 v[44:45], v[122:123], v[44:45]
	v_pk_add_f32 v[108:109], v[108:109], 1.0 op_sel_hi:[1,0]
	v_pk_mul_f32 v[44:45], v[12:13], v[44:45]
	v_pk_fma_f32 v[44:45], v[108:109], v[44:45], v[92:93]
	v_cvt_pk_bf16_f32 v124, v42, v43
	v_cvt_pk_bf16_f32 v125, v44, v45
	global_store_dwordx2 v2, v[124:125], s[8:9]
	v_pk_mul_f32 v[46:47], v[122:123], v[46:47]
	v_pk_add_f32 v[110:111], v[110:111], 1.0 op_sel_hi:[1,0]
	v_pk_mul_f32 v[46:47], v[14:15], v[46:47]
	v_pk_fma_f32 v[46:47], v[110:111], v[46:47], v[94:95]
	v_pk_mul_f32 v[48:49], v[122:123], v[48:49]
	v_pk_add_f32 v[112:113], v[112:113], 1.0 op_sel_hi:[1,0]
	v_pk_mul_f32 v[48:49], v[16:17], v[48:49]
	v_pk_fma_f32 v[48:49], v[112:113], v[48:49], v[96:97]
	v_cvt_pk_bf16_f32 v126, v46, v47
	v_cvt_pk_bf16_f32 v127, v48, v49
	global_store_dwordx2 v2, v[126:127], s[8:9] offset:512
	v_pk_mul_f32 v[50:51], v[122:123], v[50:51]
	v_pk_add_f32 v[114:115], v[114:115], 1.0 op_sel_hi:[1,0]
	v_pk_mul_f32 v[50:51], v[18:19], v[50:51]
	v_pk_fma_f32 v[50:51], v[114:115], v[50:51], v[98:99]
	v_pk_mul_f32 v[52:53], v[122:123], v[52:53]
	v_pk_add_f32 v[116:117], v[116:117], 1.0 op_sel_hi:[1,0]
	v_pk_mul_f32 v[52:53], v[20:21], v[52:53]
	v_pk_fma_f32 v[52:53], v[116:117], v[52:53], v[100:101]
	v_cvt_pk_bf16_f32 v124, v50, v51
	v_cvt_pk_bf16_f32 v125, v52, v53
	global_store_dwordx2 v2, v[124:125], s[8:9] offset:1024
	v_pk_mul_f32 v[54:55], v[122:123], v[54:55]
	v_pk_add_f32 v[118:119], v[118:119], 1.0 op_sel_hi:[1,0]
	v_pk_mul_f32 v[54:55], v[22:23], v[54:55]
	v_pk_fma_f32 v[54:55], v[118:119], v[54:55], v[102:103]
	v_pk_mul_f32 v[56:57], v[122:123], v[56:57]
	v_pk_add_f32 v[120:121], v[120:121], 1.0 op_sel_hi:[1,0]
	v_pk_mul_f32 v[56:57], v[24:25], v[56:57]
	v_pk_fma_f32 v[56:57], v[120:121], v[56:57], v[104:105]
	v_cvt_pk_bf16_f32 v126, v54, v55
	v_cvt_pk_bf16_f32 v127, v56, v57
	global_store_dwordx2 v2, v[126:127], s[8:9] offset:1536
	s_mov_b32 s1, s10
	s_branch .Lp8_loop

.Lp8_done:
.LBB0_992:
	v_writelane_b32 v254, s12, 47
	s_mov_b64 s[0:1], 0
	s_nop 0
	v_writelane_b32 v254, s13, 48
